# S step with both groups of a wave active (no causal mask): fused path, every K/V fragment read once and used for both groups, tile processed in two 32-key halves
# baseline (speedup 1.0000x reference)
.Lsb16_step_0:
	s_and_b32 s38, s25, 63
	v_readlane_b32 s32, v136, s38
	v_readlane_b32 s38, v137, s38
	s_bitcmp1_b32 s25, 6
	s_cselect_b32 s77, s38, s32
	s_and_b32 s56, s77, s86
	s_and_b32 s57, s77, s87
	s_or_b32 s28, s56, s57
	s_cmp_eq_u32 s28, 0
	s_cbranch_scc1 .Lsb16_idle_0
	s_and_b32 s38, s25, 63
	v_readlane_b32 s32, v133, s38
	v_readlane_b32 s38, v148, s38
	s_bitcmp1_b32 s25, 6
	s_cselect_b32 s76, s38, s32
	s_cmp_eq_u32 s56, 0
	s_cbranch_scc1 .Lsb16_seq_0
	s_cmp_eq_u32 s57, 0
	s_cbranch_scc1 .Lsb16_seq_0
	s_cmp_eq_u32 s76, s72
	s_cbranch_scc1 .Lsb16_seq_0
	ds_read_b128 v[50:53], v234
	ds_read_b128 v[54:57], v234 offset:64
	ds_read_b128 v[58:61], v234 offset:2304
	ds_read_b128 v[62:65], v234 offset:2368
	s_add_i32 s58, s25, 1
	s_cmp_ge_u32 s58, s101
	s_cbranch_scc1 .Lsb16_nost_f_0
	s_add_i32 s58, s25, 2
	s_cmp_ge_u32 s58, s101
	s_cbranch_scc1 .Lsb16_w0_f_0
	s_waitcnt vmcnt(4)
	s_branch .Lsb16_wr_f_0

.Lsb16_done_f_0:
	v_subrev_u32_e32 v146, s94, v236
	v_lshrrev_b32_e64 v145, v146, s77
	v_and_b32_e32 v146, 1, v145
	v_bfe_u32 v145, v145, 2, 1
	v_cmp_ne_u32_e32 vcc, 0, v146
	v_cmp_ne_u32_e64 s[28:29], 0, v145
	s_nop 0
	v_cndmask_b32_e32 v146, v213, v100, vcc
	v_cndmask_b32_e64 v145, v213, v100, s[28:29]
	s_waitcnt lgkmcnt(7)
	v_mfma_f32_16x16x32_bf16 v[34:37], v[50:53], v[66:69], 0
	v_mfma_f32_16x16x32_bf16 v[42:45], v[50:53], v[74:77], 0
	s_waitcnt lgkmcnt(6)
	v_mfma_f32_16x16x32_bf16 v[34:37], v[54:57], v[70:73], v[34:37]
	v_mfma_f32_16x16x32_bf16 v[42:45], v[54:57], v[78:81], v[42:45]
	s_waitcnt lgkmcnt(5)
	v_mfma_f32_16x16x32_bf16 v[38:41], v[58:61], v[66:69], 0
	v_mfma_f32_16x16x32_bf16 v[46:49], v[58:61], v[74:77], 0
	s_waitcnt lgkmcnt(4)
	v_mfma_f32_16x16x32_bf16 v[38:41], v[62:65], v[70:73], v[38:41]
	v_mfma_f32_16x16x32_bf16 v[46:49], v[62:65], v[78:81], v[46:49]
	ds_read_b128 v[50:53], v234 offset:9216
	ds_read_b128 v[54:57], v234 offset:11520
	ds_read_b128 v[58:61], v234 offset:13824
	ds_read_b128 v[62:65], v234 offset:16128
	v_fma_f32 v34, v34, s48, v146
	v_fma_f32 v35, v35, s48, v146
	v_fma_f32 v36, v36, s48, v146
	v_fma_f32 v37, v37, s48, v146
	v_fma_f32 v38, v38, s48, v146
	v_fma_f32 v39, v39, s48, v146
	v_fma_f32 v40, v40, s48, v146
	v_fma_f32 v41, v41, s48, v146
	v_fma_f32 v42, v42, s48, v145
	v_fma_f32 v43, v43, s48, v145
	v_fma_f32 v44, v44, s48, v145
	v_fma_f32 v45, v45, s48, v145
	v_fma_f32 v46, v46, s48, v145
	v_fma_f32 v47, v47, s48, v145
	v_fma_f32 v48, v48, s48, v145
	v_fma_f32 v49, v49, s48, v145
	v_exp_f32_e32 v34, v34
	v_exp_f32_e32 v35, v35
	v_exp_f32_e32 v36, v36
	v_exp_f32_e32 v37, v37
	v_exp_f32_e32 v38, v38
	v_exp_f32_e32 v39, v39
	v_exp_f32_e32 v40, v40
	v_exp_f32_e32 v41, v41
	v_exp_f32_e32 v42, v42
	v_exp_f32_e32 v43, v43
	v_exp_f32_e32 v44, v44
	v_exp_f32_e32 v45, v45
	v_exp_f32_e32 v46, v46
	v_exp_f32_e32 v47, v47
	v_exp_f32_e32 v48, v48
	v_exp_f32_e32 v49, v49
	v_add_f32_e32 v138, v34, v35
	v_add_f32_e32 v139, v36, v37
	v_add_f32_e32 v138, v138, v38
	v_add_f32_e32 v139, v139, v39
	v_add_f32_e32 v138, v138, v40
	v_add_f32_e32 v139, v139, v41
	v_add_f32_e32 v138, v138, v139
	v_add_f32_e32 v129, v129, v138
	v_add_f32_e32 v140, v42, v43
	v_add_f32_e32 v141, v44, v45
	v_add_f32_e32 v140, v140, v46
	v_add_f32_e32 v141, v141, v47
	v_add_f32_e32 v140, v140, v48
	v_add_f32_e32 v141, v141, v49
	v_add_f32_e32 v140, v140, v141
	v_add_f32_e32 v235, v235, v140
	v_cvt_pk_bf16_f32 v138, v34, v35
	v_cvt_pk_bf16_f32 v139, v36, v37
	v_cvt_pk_bf16_f32 v140, v38, v39
	v_cvt_pk_bf16_f32 v141, v40, v41
	v_cvt_pk_bf16_f32 v142, v42, v43
	v_cvt_pk_bf16_f32 v143, v44, v45
	v_cvt_pk_bf16_f32 v144, v46, v47
	v_cvt_pk_bf16_f32 v145, v48, v49
	s_waitcnt lgkmcnt(3)
	v_mfma_f32_16x16x32_bf16 v[2:5], v[50:53], v[138:141], v[2:5]
	v_mfma_f32_16x16x32_bf16 v[18:21], v[50:53], v[142:145], v[18:21]
	ds_read_b128 v[50:53], v234 offset:4608
	s_waitcnt lgkmcnt(3)
	v_mfma_f32_16x16x32_bf16 v[6:9], v[54:57], v[138:141], v[6:9]
	v_mfma_f32_16x16x32_bf16 v[22:25], v[54:57], v[142:145], v[22:25]
	ds_read_b128 v[54:57], v234 offset:4672
	s_waitcnt lgkmcnt(3)
	v_mfma_f32_16x16x32_bf16 v[10:13], v[58:61], v[138:141], v[10:13]
	v_mfma_f32_16x16x32_bf16 v[26:29], v[58:61], v[142:145], v[26:29]
	ds_read_b128 v[58:61], v234 offset:6912
	s_waitcnt lgkmcnt(3)
	v_mfma_f32_16x16x32_bf16 v[14:17], v[62:65], v[138:141], v[14:17]
	v_mfma_f32_16x16x32_bf16 v[30:33], v[62:65], v[142:145], v[30:33]
	ds_read_b128 v[62:65], v234 offset:6976
	s_waitcnt lgkmcnt(3)
	v_mfma_f32_16x16x32_bf16 v[34:37], v[50:53], v[66:69], 0
	v_mfma_f32_16x16x32_bf16 v[42:45], v[50:53], v[74:77], 0
	s_waitcnt lgkmcnt(2)
	v_mfma_f32_16x16x32_bf16 v[34:37], v[54:57], v[70:73], v[34:37]
	v_mfma_f32_16x16x32_bf16 v[42:45], v[54:57], v[78:81], v[42:45]
	s_waitcnt lgkmcnt(1)
	v_mfma_f32_16x16x32_bf16 v[38:41], v[58:61], v[66:69], 0
	v_mfma_f32_16x16x32_bf16 v[46:49], v[58:61], v[74:77], 0
	s_waitcnt lgkmcnt(0)
	v_mfma_f32_16x16x32_bf16 v[38:41], v[62:65], v[70:73], v[38:41]
	v_mfma_f32_16x16x32_bf16 v[46:49], v[62:65], v[78:81], v[46:49]
	ds_read_b128 v[50:53], v234 offset:9280
	ds_read_b128 v[54:57], v234 offset:11584
	ds_read_b128 v[58:61], v234 offset:13888
	ds_read_b128 v[62:65], v234 offset:16192
	v_subrev_u32_e32 v146, s94, v236
	v_lshrrev_b32_e64 v145, v146, s77
	v_and_b32_e32 v146, 1, v145
	v_bfe_u32 v145, v145, 2, 1
	v_cmp_ne_u32_e32 vcc, 0, v146
	v_cmp_ne_u32_e64 s[28:29], 0, v145
	s_nop 0
	v_cndmask_b32_e32 v146, v213, v100, vcc
	v_cndmask_b32_e64 v145, v213, v100, s[28:29]
	v_fma_f32 v34, v34, s48, v146
	v_fma_f32 v35, v35, s48, v146
	v_fma_f32 v36, v36, s48, v146
	v_fma_f32 v37, v37, s48, v146
	v_fma_f32 v38, v38, s48, v146
	v_fma_f32 v39, v39, s48, v146
	v_fma_f32 v40, v40, s48, v146
	v_fma_f32 v41, v41, s48, v146
	v_fma_f32 v42, v42, s48, v145
	v_fma_f32 v43, v43, s48, v145
	v_fma_f32 v44, v44, s48, v145
	v_fma_f32 v45, v45, s48, v145
	v_fma_f32 v46, v46, s48, v145
	v_fma_f32 v47, v47, s48, v145
	v_fma_f32 v48, v48, s48, v145
	v_fma_f32 v49, v49, s48, v145
	v_exp_f32_e32 v34, v34
	v_exp_f32_e32 v35, v35
	v_exp_f32_e32 v36, v36
	v_exp_f32_e32 v37, v37
	v_exp_f32_e32 v38, v38
	v_exp_f32_e32 v39, v39
	v_exp_f32_e32 v40, v40
	v_exp_f32_e32 v41, v41
	v_exp_f32_e32 v42, v42
	v_exp_f32_e32 v43, v43
	v_exp_f32_e32 v44, v44
	v_exp_f32_e32 v45, v45
	v_exp_f32_e32 v46, v46
	v_exp_f32_e32 v47, v47
	v_exp_f32_e32 v48, v48
	v_exp_f32_e32 v49, v49
	v_add_f32_e32 v138, v34, v35
	v_add_f32_e32 v139, v36, v37
	v_add_f32_e32 v138, v138, v38
	v_add_f32_e32 v139, v139, v39
	v_add_f32_e32 v138, v138, v40
	v_add_f32_e32 v139, v139, v41
	v_add_f32_e32 v138, v138, v139
	v_add_f32_e32 v129, v129, v138
	v_add_f32_e32 v140, v42, v43
	v_add_f32_e32 v141, v44, v45
	v_add_f32_e32 v140, v140, v46
	v_add_f32_e32 v141, v141, v47
	v_add_f32_e32 v140, v140, v48
	v_add_f32_e32 v141, v141, v49
	v_add_f32_e32 v140, v140, v141
	v_add_f32_e32 v235, v235, v140
	v_cvt_pk_bf16_f32 v138, v34, v35
	v_cvt_pk_bf16_f32 v139, v36, v37
	v_cvt_pk_bf16_f32 v140, v38, v39
	v_cvt_pk_bf16_f32 v141, v40, v41
	v_cvt_pk_bf16_f32 v142, v42, v43
	v_cvt_pk_bf16_f32 v143, v44, v45
	v_cvt_pk_bf16_f32 v144, v46, v47
	v_cvt_pk_bf16_f32 v145, v48, v49
	s_waitcnt lgkmcnt(3)
	v_mfma_f32_16x16x32_bf16 v[2:5], v[50:53], v[138:141], v[2:5]
	v_mfma_f32_16x16x32_bf16 v[18:21], v[50:53], v[142:145], v[18:21]
	s_waitcnt lgkmcnt(2)
	v_mfma_f32_16x16x32_bf16 v[6:9], v[54:57], v[138:141], v[6:9]
	v_mfma_f32_16x16x32_bf16 v[22:25], v[54:57], v[142:145], v[22:25]
	s_waitcnt lgkmcnt(1)
	v_mfma_f32_16x16x32_bf16 v[10:13], v[58:61], v[138:141], v[10:13]
	v_mfma_f32_16x16x32_bf16 v[26:29], v[58:61], v[142:145], v[26:29]
	s_waitcnt lgkmcnt(0)
	v_mfma_f32_16x16x32_bf16 v[14:17], v[62:65], v[138:141], v[14:17]
	v_mfma_f32_16x16x32_bf16 v[30:33], v[62:65], v[142:145], v[30:33]
	s_branch .Lsb16_end_0
.Lsb16_seq_0:
	ds_read_b128 v[50:53], v234
	ds_read_b128 v[54:57], v234 offset:64
	ds_read_b128 v[58:61], v234 offset:2304
	ds_read_b128 v[62:65], v234 offset:2368
	ds_read_b128 v[138:141], v234 offset:4608
	ds_read_b128 v[142:145], v234 offset:4672
	s_add_i32 s58, s25, 1
	s_cmp_ge_u32 s58, s101
	s_cbranch_scc1 .Lsb16_nost_a_0
	s_add_i32 s58, s25, 2
	s_cmp_ge_u32 s58, s101
	s_cbranch_scc1 .Lsb16_w0_a_0
	s_waitcnt vmcnt(4)
	s_branch .Lsb16_wr_a_0

.Lsb16_step_1:
	s_and_b32 s38, s25, 63
	v_readlane_b32 s32, v136, s38
	v_readlane_b32 s38, v137, s38
	s_bitcmp1_b32 s25, 6
	s_cselect_b32 s77, s38, s32
	s_and_b32 s56, s77, s86
	s_and_b32 s57, s77, s87
	s_or_b32 s28, s56, s57
	s_cmp_eq_u32 s28, 0
	s_cbranch_scc1 .Lsb16_idle_1
	s_and_b32 s38, s25, 63
	v_readlane_b32 s32, v133, s38
	v_readlane_b32 s38, v148, s38
	s_bitcmp1_b32 s25, 6
	s_cselect_b32 s76, s38, s32
	s_cmp_eq_u32 s56, 0
	s_cbranch_scc1 .Lsb16_seq_1
	s_cmp_eq_u32 s57, 0
	s_cbranch_scc1 .Lsb16_seq_1
	s_cmp_eq_u32 s76, s72
	s_cbranch_scc1 .Lsb16_seq_1
	ds_read_b128 v[50:53], v234 offset:18432
	ds_read_b128 v[54:57], v234 offset:18496
	ds_read_b128 v[58:61], v234 offset:20736
	ds_read_b128 v[62:65], v234 offset:20800
	s_add_i32 s58, s25, 1
	s_cmp_ge_u32 s58, s101
	s_cbranch_scc1 .Lsb16_nost_f_1
	s_add_i32 s58, s25, 2
	s_cmp_ge_u32 s58, s101
	s_cbranch_scc1 .Lsb16_w0_f_1
	s_waitcnt vmcnt(4)
	s_branch .Lsb16_wr_f_1

.Lsb16_done_f_1:
	v_subrev_u32_e32 v146, s94, v236
	v_lshrrev_b32_e64 v145, v146, s77
	v_and_b32_e32 v146, 1, v145
	v_bfe_u32 v145, v145, 2, 1
	v_cmp_ne_u32_e32 vcc, 0, v146
	v_cmp_ne_u32_e64 s[28:29], 0, v145
	s_nop 0
	v_cndmask_b32_e32 v146, v213, v100, vcc
	v_cndmask_b32_e64 v145, v213, v100, s[28:29]
	s_waitcnt lgkmcnt(7)
	v_mfma_f32_16x16x32_bf16 v[34:37], v[50:53], v[66:69], 0
	v_mfma_f32_16x16x32_bf16 v[42:45], v[50:53], v[74:77], 0
	s_waitcnt lgkmcnt(6)
	v_mfma_f32_16x16x32_bf16 v[34:37], v[54:57], v[70:73], v[34:37]
	v_mfma_f32_16x16x32_bf16 v[42:45], v[54:57], v[78:81], v[42:45]
	s_waitcnt lgkmcnt(5)
	v_mfma_f32_16x16x32_bf16 v[38:41], v[58:61], v[66:69], 0
	v_mfma_f32_16x16x32_bf16 v[46:49], v[58:61], v[74:77], 0
	s_waitcnt lgkmcnt(4)
	v_mfma_f32_16x16x32_bf16 v[38:41], v[62:65], v[70:73], v[38:41]
	v_mfma_f32_16x16x32_bf16 v[46:49], v[62:65], v[78:81], v[46:49]
	ds_read_b128 v[50:53], v234 offset:27648
	ds_read_b128 v[54:57], v234 offset:29952
	ds_read_b128 v[58:61], v234 offset:32256
	ds_read_b128 v[62:65], v234 offset:34560
	v_fma_f32 v34, v34, s48, v146
	v_fma_f32 v35, v35, s48, v146
	v_fma_f32 v36, v36, s48, v146
	v_fma_f32 v37, v37, s48, v146
	v_fma_f32 v38, v38, s48, v146
	v_fma_f32 v39, v39, s48, v146
	v_fma_f32 v40, v40, s48, v146
	v_fma_f32 v41, v41, s48, v146
	v_fma_f32 v42, v42, s48, v145
	v_fma_f32 v43, v43, s48, v145
	v_fma_f32 v44, v44, s48, v145
	v_fma_f32 v45, v45, s48, v145
	v_fma_f32 v46, v46, s48, v145
	v_fma_f32 v47, v47, s48, v145
	v_fma_f32 v48, v48, s48, v145
	v_fma_f32 v49, v49, s48, v145
	v_exp_f32_e32 v34, v34
	v_exp_f32_e32 v35, v35
	v_exp_f32_e32 v36, v36
	v_exp_f32_e32 v37, v37
	v_exp_f32_e32 v38, v38
	v_exp_f32_e32 v39, v39
	v_exp_f32_e32 v40, v40
	v_exp_f32_e32 v41, v41
	v_exp_f32_e32 v42, v42
	v_exp_f32_e32 v43, v43
	v_exp_f32_e32 v44, v44
	v_exp_f32_e32 v45, v45
	v_exp_f32_e32 v46, v46
	v_exp_f32_e32 v47, v47
	v_exp_f32_e32 v48, v48
	v_exp_f32_e32 v49, v49
	v_add_f32_e32 v138, v34, v35
	v_add_f32_e32 v139, v36, v37
	v_add_f32_e32 v138, v138, v38
	v_add_f32_e32 v139, v139, v39
	v_add_f32_e32 v138, v138, v40
	v_add_f32_e32 v139, v139, v41
	v_add_f32_e32 v138, v138, v139
	v_add_f32_e32 v129, v129, v138
	v_add_f32_e32 v140, v42, v43
	v_add_f32_e32 v141, v44, v45
	v_add_f32_e32 v140, v140, v46
	v_add_f32_e32 v141, v141, v47
	v_add_f32_e32 v140, v140, v48
	v_add_f32_e32 v141, v141, v49
	v_add_f32_e32 v140, v140, v141
	v_add_f32_e32 v235, v235, v140
	v_cvt_pk_bf16_f32 v138, v34, v35
	v_cvt_pk_bf16_f32 v139, v36, v37
	v_cvt_pk_bf16_f32 v140, v38, v39
	v_cvt_pk_bf16_f32 v141, v40, v41
	v_cvt_pk_bf16_f32 v142, v42, v43
	v_cvt_pk_bf16_f32 v143, v44, v45
	v_cvt_pk_bf16_f32 v144, v46, v47
	v_cvt_pk_bf16_f32 v145, v48, v49
	s_waitcnt lgkmcnt(3)
	v_mfma_f32_16x16x32_bf16 v[2:5], v[50:53], v[138:141], v[2:5]
	v_mfma_f32_16x16x32_bf16 v[18:21], v[50:53], v[142:145], v[18:21]
	ds_read_b128 v[50:53], v234 offset:23040
	s_waitcnt lgkmcnt(3)
	v_mfma_f32_16x16x32_bf16 v[6:9], v[54:57], v[138:141], v[6:9]
	v_mfma_f32_16x16x32_bf16 v[22:25], v[54:57], v[142:145], v[22:25]
	ds_read_b128 v[54:57], v234 offset:23104
	s_waitcnt lgkmcnt(3)
	v_mfma_f32_16x16x32_bf16 v[10:13], v[58:61], v[138:141], v[10:13]
	v_mfma_f32_16x16x32_bf16 v[26:29], v[58:61], v[142:145], v[26:29]
	ds_read_b128 v[58:61], v234 offset:25344
	s_waitcnt lgkmcnt(3)
	v_mfma_f32_16x16x32_bf16 v[14:17], v[62:65], v[138:141], v[14:17]
	v_mfma_f32_16x16x32_bf16 v[30:33], v[62:65], v[142:145], v[30:33]
	ds_read_b128 v[62:65], v234 offset:25408
	s_waitcnt lgkmcnt(3)
	v_mfma_f32_16x16x32_bf16 v[34:37], v[50:53], v[66:69], 0
	v_mfma_f32_16x16x32_bf16 v[42:45], v[50:53], v[74:77], 0
	s_waitcnt lgkmcnt(2)
	v_mfma_f32_16x16x32_bf16 v[34:37], v[54:57], v[70:73], v[34:37]
	v_mfma_f32_16x16x32_bf16 v[42:45], v[54:57], v[78:81], v[42:45]
	s_waitcnt lgkmcnt(1)
	v_mfma_f32_16x16x32_bf16 v[38:41], v[58:61], v[66:69], 0
	v_mfma_f32_16x16x32_bf16 v[46:49], v[58:61], v[74:77], 0
	s_waitcnt lgkmcnt(0)
	v_mfma_f32_16x16x32_bf16 v[38:41], v[62:65], v[70:73], v[38:41]
	v_mfma_f32_16x16x32_bf16 v[46:49], v[62:65], v[78:81], v[46:49]
	ds_read_b128 v[50:53], v234 offset:27712
	ds_read_b128 v[54:57], v234 offset:30016
	ds_read_b128 v[58:61], v234 offset:32320
	ds_read_b128 v[62:65], v234 offset:34624
	v_subrev_u32_e32 v146, s94, v236
	v_lshrrev_b32_e64 v145, v146, s77
	v_and_b32_e32 v146, 1, v145
	v_bfe_u32 v145, v145, 2, 1
	v_cmp_ne_u32_e32 vcc, 0, v146
	v_cmp_ne_u32_e64 s[28:29], 0, v145
	s_nop 0
	v_cndmask_b32_e32 v146, v213, v100, vcc
	v_cndmask_b32_e64 v145, v213, v100, s[28:29]
	v_fma_f32 v34, v34, s48, v146
	v_fma_f32 v35, v35, s48, v146
	v_fma_f32 v36, v36, s48, v146
	v_fma_f32 v37, v37, s48, v146
	v_fma_f32 v38, v38, s48, v146
	v_fma_f32 v39, v39, s48, v146
	v_fma_f32 v40, v40, s48, v146
	v_fma_f32 v41, v41, s48, v146
	v_fma_f32 v42, v42, s48, v145
	v_fma_f32 v43, v43, s48, v145
	v_fma_f32 v44, v44, s48, v145
	v_fma_f32 v45, v45, s48, v145
	v_fma_f32 v46, v46, s48, v145
	v_fma_f32 v47, v47, s48, v145
	v_fma_f32 v48, v48, s48, v145
	v_fma_f32 v49, v49, s48, v145
	v_exp_f32_e32 v34, v34
	v_exp_f32_e32 v35, v35
	v_exp_f32_e32 v36, v36
	v_exp_f32_e32 v37, v37
	v_exp_f32_e32 v38, v38
	v_exp_f32_e32 v39, v39
	v_exp_f32_e32 v40, v40
	v_exp_f32_e32 v41, v41
	v_exp_f32_e32 v42, v42
	v_exp_f32_e32 v43, v43
	v_exp_f32_e32 v44, v44
	v_exp_f32_e32 v45, v45
	v_exp_f32_e32 v46, v46
	v_exp_f32_e32 v47, v47
	v_exp_f32_e32 v48, v48
	v_exp_f32_e32 v49, v49
	v_add_f32_e32 v138, v34, v35
	v_add_f32_e32 v139, v36, v37
	v_add_f32_e32 v138, v138, v38
	v_add_f32_e32 v139, v139, v39
	v_add_f32_e32 v138, v138, v40
	v_add_f32_e32 v139, v139, v41
	v_add_f32_e32 v138, v138, v139
	v_add_f32_e32 v129, v129, v138
	v_add_f32_e32 v140, v42, v43
	v_add_f32_e32 v141, v44, v45
	v_add_f32_e32 v140, v140, v46
	v_add_f32_e32 v141, v141, v47
	v_add_f32_e32 v140, v140, v48
	v_add_f32_e32 v141, v141, v49
	v_add_f32_e32 v140, v140, v141
	v_add_f32_e32 v235, v235, v140
	v_cvt_pk_bf16_f32 v138, v34, v35
	v_cvt_pk_bf16_f32 v139, v36, v37
	v_cvt_pk_bf16_f32 v140, v38, v39
	v_cvt_pk_bf16_f32 v141, v40, v41
	v_cvt_pk_bf16_f32 v142, v42, v43
	v_cvt_pk_bf16_f32 v143, v44, v45
	v_cvt_pk_bf16_f32 v144, v46, v47
	v_cvt_pk_bf16_f32 v145, v48, v49
	s_waitcnt lgkmcnt(3)
	v_mfma_f32_16x16x32_bf16 v[2:5], v[50:53], v[138:141], v[2:5]
	v_mfma_f32_16x16x32_bf16 v[18:21], v[50:53], v[142:145], v[18:21]
	s_waitcnt lgkmcnt(2)
	v_mfma_f32_16x16x32_bf16 v[6:9], v[54:57], v[138:141], v[6:9]
	v_mfma_f32_16x16x32_bf16 v[22:25], v[54:57], v[142:145], v[22:25]
	s_waitcnt lgkmcnt(1)
	v_mfma_f32_16x16x32_bf16 v[10:13], v[58:61], v[138:141], v[10:13]
	v_mfma_f32_16x16x32_bf16 v[26:29], v[58:61], v[142:145], v[26:29]
	s_waitcnt lgkmcnt(0)
	v_mfma_f32_16x16x32_bf16 v[14:17], v[62:65], v[138:141], v[14:17]
	v_mfma_f32_16x16x32_bf16 v[30:33], v[62:65], v[142:145], v[30:33]
	s_branch .Lsb16_end_1
.Lsb16_seq_1:
	ds_read_b128 v[50:53], v234 offset:18432
	ds_read_b128 v[54:57], v234 offset:18496
	ds_read_b128 v[58:61], v234 offset:20736
	ds_read_b128 v[62:65], v234 offset:20800
	ds_read_b128 v[138:141], v234 offset:23040
	ds_read_b128 v[142:145], v234 offset:23104
	s_add_i32 s58, s25, 1
	s_cmp_ge_u32 s58, s101
	s_cbranch_scc1 .Lsb16_nost_a_1
	s_add_i32 s58, s25, 2
	s_cmp_ge_u32 s58, s101
	s_cbranch_scc1 .Lsb16_w0_a_1
	s_waitcnt vmcnt(4)
	s_branch .Lsb16_wr_a_1
